# L1 invalidate (acquire) issued at barrier arrival so its latency overlaps the arrive/poll round trips; same for outproj's panel acquire
# speedup vs baseline: 1.0082x; 1.0048x over previous
.Lop_tile:
	s_and_b32 s0, s78, 3
	s_or_b32 s0, s0, s77
	v_readlane_b32 s12, v253, 5
	v_readlane_b32 s13, v253, 6
	s_lshl_b32 s2, s0, 2
	s_add_u32 s2, s2, 0x100
	v_mov_b32_e32 v170, s2
	s_add_i32 s3, s82, 1
	s_lshl_b32 s3, s3, 3
	s_movk_i32 s14, 0x1000
	s_cmp_lg_u32 s76, 0
	s_cbranch_scc1 .Lop_acqw
	s_nop 2
	buffer_inv sc1
.Lop_acqp:
	global_load_dword v171, v170, s[12:13] sc1
	s_waitcnt vmcnt(0)
	v_readfirstlane_b32 s15, v171
	s_cmp_ge_u32 s15, s3
	s_cbranch_scc1 .Lop_acqok
	s_sleep 1
	s_add_i32 s14, s14, -1
	s_cmp_lg_u32 s14, 0
	s_cbranch_scc1 .Lop_acqp
.Lop_acqok:
	s_waitcnt vmcnt(0)
.Lop_acqw:
	s_barrier
	s_lshr_b32 s1, s78, 2
	s_lshl_b32 s1, s1, 7
	s_lshl_b32 s2, s0, 8
	s_mul_i32 s3, s2, 0x800
	s_add_u32 s68, s18, s3
	s_addc_u32 s69, s19, 0
	s_mul_i32 s3, s1, 0x800
	s_add_u32 s70, s80, s3
	s_addc_u32 s71, s81, 0
	s_lshl_b32 s3, s2, 11
	s_lshl_b32 s12, s1, 1
	s_add_u32 s3, s3, s12
	s_add_u32 s74, s24, s3
	s_addc_u32 s75, s25, 0
	s_add_i32 s12, s0, -12
	s_lshr_b32 s12, s12, 2
	s_cmp_lt_u32 s0, 16
	s_cselect_b32 s12, 0, s12
	s_cselect_b32 s14, s52, s54
	s_cselect_b32 s15, s53, s55
	s_mul_i32 s13, s82, 5
	s_add_i32 s12, s12, s13
	s_mul_i32 s12, s12, 0x6000
	s_add_u32 s12, s12, 0x2000
	s_lshl_b32 s13, s1, 2
	s_add_u32 s12, s12, s13
	s_add_u32 s72, s30, s12
	s_addc_u32 s73, s31, 0
	s_and_b32 s12, s0, 15
	s_lshl_b32 s12, s12, 20
	s_add_u32 s12, s12, s13
	s_add_u32 s14, s14, s12
	s_addc_u32 s15, s15, 0
	s_cmp_eq_u32 s82, 0
	s_cselect_b32 s14, s14, s74
	s_cselect_b32 s15, s15, s75
	s_cselect_b32 s38, 64, 32
	s_cselect_b64 vcc, -1, 0
	s_lshl_b32 s39, s38, 1
	s_add_u32 s40, s39, s38
	v_cndmask_b32_e32 v191, v206, v210, vcc
	v_cndmask_b32_e32 v192, v207, v211, vcc
	v_cndmask_b32_e32 v193, v208, v168, vcc
	v_cndmask_b32_e32 v244, v209, v169, vcc
	s_add_u32 m0, s76, 0x0
	s_nop 0
	global_load_lds_dwordx4 v196, s[68:69]
	s_add_u32 m0, s76, 0x2000
	s_nop 0
	global_load_lds_dwordx4 v197, s[68:69]
	s_add_u32 m0, s76, 0x4000
	s_nop 0
	global_load_lds_dwordx4 v198, s[68:69]
	s_add_u32 m0, s76, 0x6000
	s_nop 0
	global_load_lds_dwordx4 v199, s[68:69]
	s_add_u32 m0, s76, 0x8000
	s_nop 0
	global_load_lds_dwordx4 v196, s[70:71]
	s_add_u32 m0, s76, 0xa000
	s_nop 0
	global_load_lds_dwordx4 v197, s[70:71]
	s_add_u32 s68, s68, 0x80
	s_addc_u32 s69, s69, 0
	s_add_u32 s70, s70, 0x80
	s_addc_u32 s71, s71, 0
	s_add_u32 m0, s76, 0xc000
	s_nop 0
	global_load_lds_dwordx4 v196, s[68:69]
	s_add_u32 m0, s76, 0xe000
	s_nop 0
	global_load_lds_dwordx4 v197, s[68:69]
	s_add_u32 m0, s76, 0x10000
	s_nop 0
	global_load_lds_dwordx4 v198, s[68:69]
	s_add_u32 m0, s76, 0x12000
	s_nop 0
	global_load_lds_dwordx4 v199, s[68:69]
	s_add_u32 m0, s76, 0x14000
	s_nop 0
	global_load_lds_dwordx4 v196, s[70:71]
	s_add_u32 m0, s76, 0x16000
	s_nop 0
	global_load_lds_dwordx4 v197, s[70:71]
	s_add_u32 s68, s68, 0x80
	s_addc_u32 s69, s69, 0
	s_add_u32 s70, s70, 0x80
	s_addc_u32 s71, s71, 0
	s_waitcnt vmcnt(6)
	s_barrier
	s_cmp_ge_u32 s76, 0x1000
	s_cbranch_scc1 .Lop_streamB
	v_add_u32_e32 v204, 0x0, v200
	v_add_u32_e32 v205, 0x0, v202
	ds_read_b128 v[130:133], v204 offset:0
	ds_read_b128 v[134:137], v204 offset:2048
	ds_read_b128 v[138:141], v204 offset:4096
	ds_read_b128 v[142:145], v204 offset:6144
	ds_read_b128 v[146:149], v205 offset:0
	ds_read_b128 v[150:153], v205 offset:2048
	ds_read_b128 v[154:157], v205 offset:4096
	ds_read_b128 v[158:161], v205 offset:6144
	v_add_u32_e32 v204, 0x0, v201
	v_add_u32_e32 v205, 0x0, v203
	ds_read_b128 v[212:215], v204 offset:0
	ds_read_b128 v[216:219], v204 offset:2048
	ds_read_b128 v[220:223], v204 offset:4096
	ds_read_b128 v[224:227], v204 offset:6144
	ds_read_b128 v[228:231], v205 offset:0
	ds_read_b128 v[232:235], v205 offset:2048
	ds_read_b128 v[236:239], v205 offset:4096
	ds_read_b128 v[240:243], v205 offset:6144
	s_add_u32 m0, s76, 0x18000
	s_nop 0
	global_load_lds_dwordx4 v196, s[68:69]
	s_add_u32 m0, s76, 0x1a000
	s_nop 0
	global_load_lds_dwordx4 v197, s[68:69]
	s_add_u32 m0, s76, 0x1c000
	s_nop 0
	global_load_lds_dwordx4 v198, s[68:69]
	s_add_u32 m0, s76, 0x1e000
	s_nop 0
	global_load_lds_dwordx4 v199, s[68:69]
	s_add_u32 m0, s76, 0x20000
	s_nop 0
	global_load_lds_dwordx4 v196, s[70:71]
	s_add_u32 m0, s76, 0x22000
	s_nop 0
	global_load_lds_dwordx4 v197, s[70:71]
	s_add_u32 s68, s68, 0x80
	s_addc_u32 s69, s69, 0
	s_add_u32 s70, s70, 0x80
	s_addc_u32 s71, s71, 0
	global_load_dwordx4 v[174:177], v190, s[72:73] offset:0
	global_load_dwordx4 v[178:181], v190, s[72:73] offset:64
	s_waitcnt lgkmcnt(0)
	s_barrier
	v_mfma_f32_16x16x32_bf16 v[2:5], v[146:149], v[130:133], 0
	v_mfma_f32_16x16x32_bf16 v[6:9], v[150:153], v[130:133], 0
	v_mfma_f32_16x16x32_bf16 v[10:13], v[154:157], v[130:133], 0
	v_mfma_f32_16x16x32_bf16 v[14:17], v[158:161], v[130:133], 0
	v_mfma_f32_16x16x32_bf16 v[18:21], v[146:149], v[134:137], 0
	v_mfma_f32_16x16x32_bf16 v[22:25], v[150:153], v[134:137], 0
	v_mfma_f32_16x16x32_bf16 v[26:29], v[154:157], v[134:137], 0
	v_mfma_f32_16x16x32_bf16 v[30:33], v[158:161], v[134:137], 0
	v_mfma_f32_16x16x32_bf16 v[34:37], v[146:149], v[138:141], 0
	v_mfma_f32_16x16x32_bf16 v[38:41], v[150:153], v[138:141], 0
	v_mfma_f32_16x16x32_bf16 v[42:45], v[154:157], v[138:141], 0
	v_mfma_f32_16x16x32_bf16 v[46:49], v[158:161], v[138:141], 0
	v_mfma_f32_16x16x32_bf16 v[50:53], v[146:149], v[142:145], 0
	v_mfma_f32_16x16x32_bf16 v[54:57], v[150:153], v[142:145], 0
	v_mfma_f32_16x16x32_bf16 v[58:61], v[154:157], v[142:145], 0
	v_mfma_f32_16x16x32_bf16 v[62:65], v[158:161], v[142:145], 0
	v_mfma_f32_16x16x32_bf16 v[2:5], v[228:231], v[212:215], v[2:5]
	v_mfma_f32_16x16x32_bf16 v[6:9], v[232:235], v[212:215], v[6:9]
	v_mfma_f32_16x16x32_bf16 v[10:13], v[236:239], v[212:215], v[10:13]
	v_mfma_f32_16x16x32_bf16 v[14:17], v[240:243], v[212:215], v[14:17]
	v_mfma_f32_16x16x32_bf16 v[18:21], v[228:231], v[216:219], v[18:21]
	v_mfma_f32_16x16x32_bf16 v[22:25], v[232:235], v[216:219], v[22:25]
	v_mfma_f32_16x16x32_bf16 v[26:29], v[236:239], v[216:219], v[26:29]
	v_mfma_f32_16x16x32_bf16 v[30:33], v[240:243], v[216:219], v[30:33]
	v_mfma_f32_16x16x32_bf16 v[34:37], v[228:231], v[220:223], v[34:37]
	v_mfma_f32_16x16x32_bf16 v[38:41], v[232:235], v[220:223], v[38:41]
	v_mfma_f32_16x16x32_bf16 v[42:45], v[236:239], v[220:223], v[42:45]
	v_mfma_f32_16x16x32_bf16 v[46:49], v[240:243], v[220:223], v[46:49]
	v_mfma_f32_16x16x32_bf16 v[50:53], v[228:231], v[224:227], v[50:53]
	v_mfma_f32_16x16x32_bf16 v[54:57], v[232:235], v[224:227], v[54:57]
	v_mfma_f32_16x16x32_bf16 v[58:61], v[236:239], v[224:227], v[58:61]
	v_mfma_f32_16x16x32_bf16 v[62:65], v[240:243], v[224:227], v[62:65]
	s_waitcnt vmcnt(8)
	s_barrier
	v_add_u32_e32 v204, 0xc000, v200
	v_add_u32_e32 v205, 0xc000, v202
	ds_read_b128 v[130:133], v204 offset:0
	ds_read_b128 v[134:137], v204 offset:2048
	ds_read_b128 v[138:141], v204 offset:4096
	ds_read_b128 v[142:145], v204 offset:6144
	ds_read_b128 v[146:149], v205 offset:0
	ds_read_b128 v[150:153], v205 offset:2048
	ds_read_b128 v[154:157], v205 offset:4096
	ds_read_b128 v[158:161], v205 offset:6144
	v_add_u32_e32 v204, 0xc000, v201
	v_add_u32_e32 v205, 0xc000, v203
	ds_read_b128 v[212:215], v204 offset:0
	ds_read_b128 v[216:219], v204 offset:2048
	ds_read_b128 v[220:223], v204 offset:4096
	ds_read_b128 v[224:227], v204 offset:6144
	ds_read_b128 v[228:231], v205 offset:0
	ds_read_b128 v[232:235], v205 offset:2048
	ds_read_b128 v[236:239], v205 offset:4096
	ds_read_b128 v[240:243], v205 offset:6144
	s_add_u32 m0, s76, 0x0
	s_nop 0
	global_load_lds_dwordx4 v196, s[68:69]
	s_add_u32 m0, s76, 0x2000
	s_nop 0
	global_load_lds_dwordx4 v197, s[68:69]
	s_add_u32 m0, s76, 0x4000
	s_nop 0
	global_load_lds_dwordx4 v198, s[68:69]
	s_add_u32 m0, s76, 0x6000
	s_nop 0
	global_load_lds_dwordx4 v199, s[68:69]
	s_add_u32 m0, s76, 0x8000
	s_nop 0
	global_load_lds_dwordx4 v196, s[70:71]
	s_add_u32 m0, s76, 0xa000
	s_nop 0
	global_load_lds_dwordx4 v197, s[70:71]
	s_add_u32 s68, s68, 0x80
	s_addc_u32 s69, s69, 0
	s_add_u32 s70, s70, 0x80
	s_addc_u32 s71, s71, 0
	global_load_dwordx4 v[182:185], v190, s[72:73] offset:128
	global_load_dwordx4 v[186:189], v190, s[72:73] offset:192
	s_waitcnt lgkmcnt(0)
	s_barrier
	v_mfma_f32_16x16x32_bf16 v[2:5], v[146:149], v[130:133], v[2:5]
	v_mfma_f32_16x16x32_bf16 v[6:9], v[150:153], v[130:133], v[6:9]
	v_mfma_f32_16x16x32_bf16 v[10:13], v[154:157], v[130:133], v[10:13]
	v_mfma_f32_16x16x32_bf16 v[14:17], v[158:161], v[130:133], v[14:17]
	v_mfma_f32_16x16x32_bf16 v[18:21], v[146:149], v[134:137], v[18:21]
	v_mfma_f32_16x16x32_bf16 v[22:25], v[150:153], v[134:137], v[22:25]
	v_mfma_f32_16x16x32_bf16 v[26:29], v[154:157], v[134:137], v[26:29]
	v_mfma_f32_16x16x32_bf16 v[30:33], v[158:161], v[134:137], v[30:33]
	v_mfma_f32_16x16x32_bf16 v[34:37], v[146:149], v[138:141], v[34:37]
	v_mfma_f32_16x16x32_bf16 v[38:41], v[150:153], v[138:141], v[38:41]
	v_mfma_f32_16x16x32_bf16 v[42:45], v[154:157], v[138:141], v[42:45]
	v_mfma_f32_16x16x32_bf16 v[46:49], v[158:161], v[138:141], v[46:49]
	v_mfma_f32_16x16x32_bf16 v[50:53], v[146:149], v[142:145], v[50:53]
	v_mfma_f32_16x16x32_bf16 v[54:57], v[150:153], v[142:145], v[54:57]
	v_mfma_f32_16x16x32_bf16 v[58:61], v[154:157], v[142:145], v[58:61]
	v_mfma_f32_16x16x32_bf16 v[62:65], v[158:161], v[142:145], v[62:65]
	v_mfma_f32_16x16x32_bf16 v[2:5], v[228:231], v[212:215], v[2:5]
	v_mfma_f32_16x16x32_bf16 v[6:9], v[232:235], v[212:215], v[6:9]
	v_mfma_f32_16x16x32_bf16 v[10:13], v[236:239], v[212:215], v[10:13]
	v_mfma_f32_16x16x32_bf16 v[14:17], v[240:243], v[212:215], v[14:17]
	v_mfma_f32_16x16x32_bf16 v[18:21], v[228:231], v[216:219], v[18:21]
	v_mfma_f32_16x16x32_bf16 v[22:25], v[232:235], v[216:219], v[22:25]
	v_mfma_f32_16x16x32_bf16 v[26:29], v[236:239], v[216:219], v[26:29]
	v_mfma_f32_16x16x32_bf16 v[30:33], v[240:243], v[216:219], v[30:33]
	v_mfma_f32_16x16x32_bf16 v[34:37], v[228:231], v[220:223], v[34:37]
	v_mfma_f32_16x16x32_bf16 v[38:41], v[232:235], v[220:223], v[38:41]
	v_mfma_f32_16x16x32_bf16 v[42:45], v[236:239], v[220:223], v[42:45]
	v_mfma_f32_16x16x32_bf16 v[46:49], v[240:243], v[220:223], v[46:49]
	v_mfma_f32_16x16x32_bf16 v[50:53], v[228:231], v[224:227], v[50:53]
	v_mfma_f32_16x16x32_bf16 v[54:57], v[232:235], v[224:227], v[54:57]
	v_mfma_f32_16x16x32_bf16 v[58:61], v[236:239], v[224:227], v[58:61]
	v_mfma_f32_16x16x32_bf16 v[62:65], v[240:243], v[224:227], v[62:65]
	s_waitcnt vmcnt(10)
	s_barrier
	v_add_u32_e32 v204, 0x18000, v200
	v_add_u32_e32 v205, 0x18000, v202
	ds_read_b128 v[130:133], v204 offset:0
	ds_read_b128 v[134:137], v204 offset:2048
	ds_read_b128 v[138:141], v204 offset:4096
	ds_read_b128 v[142:145], v204 offset:6144
	ds_read_b128 v[146:149], v205 offset:0
	ds_read_b128 v[150:153], v205 offset:2048
	ds_read_b128 v[154:157], v205 offset:4096
	ds_read_b128 v[158:161], v205 offset:6144
	v_add_u32_e32 v204, 0x18000, v201
	v_add_u32_e32 v205, 0x18000, v203
	ds_read_b128 v[212:215], v204 offset:0
	ds_read_b128 v[216:219], v204 offset:2048
	ds_read_b128 v[220:223], v204 offset:4096
	ds_read_b128 v[224:227], v204 offset:6144
	ds_read_b128 v[228:231], v205 offset:0
	ds_read_b128 v[232:235], v205 offset:2048
	ds_read_b128 v[236:239], v205 offset:4096
	ds_read_b128 v[240:243], v205 offset:6144
	s_add_u32 m0, s76, 0xc000
	s_nop 0
	global_load_lds_dwordx4 v196, s[68:69]
	s_add_u32 m0, s76, 0xe000
	s_nop 0
	global_load_lds_dwordx4 v197, s[68:69]
	s_add_u32 m0, s76, 0x10000
	s_nop 0
	global_load_lds_dwordx4 v198, s[68:69]
	s_add_u32 m0, s76, 0x12000
	s_nop 0
	global_load_lds_dwordx4 v199, s[68:69]
	s_add_u32 m0, s76, 0x14000
	s_nop 0
	global_load_lds_dwordx4 v196, s[70:71]
	s_add_u32 m0, s76, 0x16000
	s_nop 0
	global_load_lds_dwordx4 v197, s[70:71]
	s_add_u32 s68, s68, 0x80
	s_addc_u32 s69, s69, 0
	s_add_u32 s70, s70, 0x80
	s_addc_u32 s71, s71, 0
	global_load_dwordx4 v[66:69], v191, s[14:15]
	v_add_u32_e32 v170, s38, v191
	global_load_dwordx4 v[70:73], v170, s[14:15]
	s_waitcnt lgkmcnt(0)
	s_barrier
	v_mfma_f32_16x16x32_bf16 v[2:5], v[146:149], v[130:133], v[2:5]
	v_mfma_f32_16x16x32_bf16 v[6:9], v[150:153], v[130:133], v[6:9]
	v_mfma_f32_16x16x32_bf16 v[10:13], v[154:157], v[130:133], v[10:13]
	v_mfma_f32_16x16x32_bf16 v[14:17], v[158:161], v[130:133], v[14:17]
	v_mfma_f32_16x16x32_bf16 v[18:21], v[146:149], v[134:137], v[18:21]
	v_mfma_f32_16x16x32_bf16 v[22:25], v[150:153], v[134:137], v[22:25]
	v_mfma_f32_16x16x32_bf16 v[26:29], v[154:157], v[134:137], v[26:29]
	v_mfma_f32_16x16x32_bf16 v[30:33], v[158:161], v[134:137], v[30:33]
	v_mfma_f32_16x16x32_bf16 v[34:37], v[146:149], v[138:141], v[34:37]
	v_mfma_f32_16x16x32_bf16 v[38:41], v[150:153], v[138:141], v[38:41]
	v_mfma_f32_16x16x32_bf16 v[42:45], v[154:157], v[138:141], v[42:45]
	v_mfma_f32_16x16x32_bf16 v[46:49], v[158:161], v[138:141], v[46:49]
	v_mfma_f32_16x16x32_bf16 v[50:53], v[146:149], v[142:145], v[50:53]
	v_mfma_f32_16x16x32_bf16 v[54:57], v[150:153], v[142:145], v[54:57]
	v_mfma_f32_16x16x32_bf16 v[58:61], v[154:157], v[142:145], v[58:61]
	v_mfma_f32_16x16x32_bf16 v[62:65], v[158:161], v[142:145], v[62:65]
	v_mfma_f32_16x16x32_bf16 v[2:5], v[228:231], v[212:215], v[2:5]
	v_mfma_f32_16x16x32_bf16 v[6:9], v[232:235], v[212:215], v[6:9]
	v_mfma_f32_16x16x32_bf16 v[10:13], v[236:239], v[212:215], v[10:13]
	v_mfma_f32_16x16x32_bf16 v[14:17], v[240:243], v[212:215], v[14:17]
	v_mfma_f32_16x16x32_bf16 v[18:21], v[228:231], v[216:219], v[18:21]
	v_mfma_f32_16x16x32_bf16 v[22:25], v[232:235], v[216:219], v[22:25]
	v_mfma_f32_16x16x32_bf16 v[26:29], v[236:239], v[216:219], v[26:29]
	v_mfma_f32_16x16x32_bf16 v[30:33], v[240:243], v[216:219], v[30:33]
	v_mfma_f32_16x16x32_bf16 v[34:37], v[228:231], v[220:223], v[34:37]
	v_mfma_f32_16x16x32_bf16 v[38:41], v[232:235], v[220:223], v[38:41]
	v_mfma_f32_16x16x32_bf16 v[42:45], v[236:239], v[220:223], v[42:45]
	v_mfma_f32_16x16x32_bf16 v[46:49], v[240:243], v[220:223], v[46:49]
	v_mfma_f32_16x16x32_bf16 v[50:53], v[228:231], v[224:227], v[50:53]
	v_mfma_f32_16x16x32_bf16 v[54:57], v[232:235], v[224:227], v[54:57]
	v_mfma_f32_16x16x32_bf16 v[58:61], v[236:239], v[224:227], v[58:61]
	v_mfma_f32_16x16x32_bf16 v[62:65], v[240:243], v[224:227], v[62:65]
	s_waitcnt vmcnt(10)
	s_barrier
	v_add_u32_e32 v204, 0x0, v200
	v_add_u32_e32 v205, 0x0, v202
	ds_read_b128 v[130:133], v204 offset:0
	ds_read_b128 v[134:137], v204 offset:2048
	ds_read_b128 v[138:141], v204 offset:4096
	ds_read_b128 v[142:145], v204 offset:6144
	ds_read_b128 v[146:149], v205 offset:0
	ds_read_b128 v[150:153], v205 offset:2048
	ds_read_b128 v[154:157], v205 offset:4096
	ds_read_b128 v[158:161], v205 offset:6144
	v_add_u32_e32 v204, 0x0, v201
	v_add_u32_e32 v205, 0x0, v203
	ds_read_b128 v[212:215], v204 offset:0
	ds_read_b128 v[216:219], v204 offset:2048
	ds_read_b128 v[220:223], v204 offset:4096
	ds_read_b128 v[224:227], v204 offset:6144
	ds_read_b128 v[228:231], v205 offset:0
	ds_read_b128 v[232:235], v205 offset:2048
	ds_read_b128 v[236:239], v205 offset:4096
	ds_read_b128 v[240:243], v205 offset:6144
	s_add_u32 m0, s76, 0x18000
	s_nop 0
	global_load_lds_dwordx4 v196, s[68:69]
	s_add_u32 m0, s76, 0x1a000
	s_nop 0
	global_load_lds_dwordx4 v197, s[68:69]
	s_add_u32 m0, s76, 0x1c000
	s_nop 0
	global_load_lds_dwordx4 v198, s[68:69]
	s_add_u32 m0, s76, 0x1e000
	s_nop 0
	global_load_lds_dwordx4 v199, s[68:69]
	s_add_u32 m0, s76, 0x20000
	s_nop 0
	global_load_lds_dwordx4 v196, s[70:71]
	s_add_u32 m0, s76, 0x22000
	s_nop 0
	global_load_lds_dwordx4 v197, s[70:71]
	s_add_u32 s68, s68, 0x80
	s_addc_u32 s69, s69, 0
	s_add_u32 s70, s70, 0x80
	s_addc_u32 s71, s71, 0
	v_add_u32_e32 v170, s39, v191
	global_load_dwordx4 v[74:77], v170, s[14:15]
	v_add_u32_e32 v170, s40, v191
	global_load_dwordx4 v[78:81], v170, s[14:15]
	s_waitcnt lgkmcnt(0)
	s_barrier
	v_mfma_f32_16x16x32_bf16 v[2:5], v[146:149], v[130:133], v[2:5]
	v_mfma_f32_16x16x32_bf16 v[6:9], v[150:153], v[130:133], v[6:9]
	v_mfma_f32_16x16x32_bf16 v[10:13], v[154:157], v[130:133], v[10:13]
	v_mfma_f32_16x16x32_bf16 v[14:17], v[158:161], v[130:133], v[14:17]
	v_mfma_f32_16x16x32_bf16 v[18:21], v[146:149], v[134:137], v[18:21]
	v_mfma_f32_16x16x32_bf16 v[22:25], v[150:153], v[134:137], v[22:25]
	v_mfma_f32_16x16x32_bf16 v[26:29], v[154:157], v[134:137], v[26:29]
	v_mfma_f32_16x16x32_bf16 v[30:33], v[158:161], v[134:137], v[30:33]
	v_mfma_f32_16x16x32_bf16 v[34:37], v[146:149], v[138:141], v[34:37]
	v_mfma_f32_16x16x32_bf16 v[38:41], v[150:153], v[138:141], v[38:41]
	v_mfma_f32_16x16x32_bf16 v[42:45], v[154:157], v[138:141], v[42:45]
	v_mfma_f32_16x16x32_bf16 v[46:49], v[158:161], v[138:141], v[46:49]
	v_mfma_f32_16x16x32_bf16 v[50:53], v[146:149], v[142:145], v[50:53]
	v_mfma_f32_16x16x32_bf16 v[54:57], v[150:153], v[142:145], v[54:57]
	v_mfma_f32_16x16x32_bf16 v[58:61], v[154:157], v[142:145], v[58:61]
	v_mfma_f32_16x16x32_bf16 v[62:65], v[158:161], v[142:145], v[62:65]
	v_mfma_f32_16x16x32_bf16 v[2:5], v[228:231], v[212:215], v[2:5]
	v_mfma_f32_16x16x32_bf16 v[6:9], v[232:235], v[212:215], v[6:9]
	v_mfma_f32_16x16x32_bf16 v[10:13], v[236:239], v[212:215], v[10:13]
	v_mfma_f32_16x16x32_bf16 v[14:17], v[240:243], v[212:215], v[14:17]
	v_mfma_f32_16x16x32_bf16 v[18:21], v[228:231], v[216:219], v[18:21]
	v_mfma_f32_16x16x32_bf16 v[22:25], v[232:235], v[216:219], v[22:25]
	v_mfma_f32_16x16x32_bf16 v[26:29], v[236:239], v[216:219], v[26:29]
	v_mfma_f32_16x16x32_bf16 v[30:33], v[240:243], v[216:219], v[30:33]
	v_mfma_f32_16x16x32_bf16 v[34:37], v[228:231], v[220:223], v[34:37]
	v_mfma_f32_16x16x32_bf16 v[38:41], v[232:235], v[220:223], v[38:41]
	v_mfma_f32_16x16x32_bf16 v[42:45], v[236:239], v[220:223], v[42:45]
	v_mfma_f32_16x16x32_bf16 v[46:49], v[240:243], v[220:223], v[46:49]
	v_mfma_f32_16x16x32_bf16 v[50:53], v[228:231], v[224:227], v[50:53]
	v_mfma_f32_16x16x32_bf16 v[54:57], v[232:235], v[224:227], v[54:57]
	v_mfma_f32_16x16x32_bf16 v[58:61], v[236:239], v[224:227], v[58:61]
	v_mfma_f32_16x16x32_bf16 v[62:65], v[240:243], v[224:227], v[62:65]
	s_waitcnt vmcnt(10)
	s_barrier
	v_add_u32_e32 v204, 0xc000, v200
	v_add_u32_e32 v205, 0xc000, v202
	ds_read_b128 v[130:133], v204 offset:0
	ds_read_b128 v[134:137], v204 offset:2048
	ds_read_b128 v[138:141], v204 offset:4096
	ds_read_b128 v[142:145], v204 offset:6144
	ds_read_b128 v[146:149], v205 offset:0
	ds_read_b128 v[150:153], v205 offset:2048
	ds_read_b128 v[154:157], v205 offset:4096
	ds_read_b128 v[158:161], v205 offset:6144
	v_add_u32_e32 v204, 0xc000, v201
	v_add_u32_e32 v205, 0xc000, v203
	ds_read_b128 v[212:215], v204 offset:0
	ds_read_b128 v[216:219], v204 offset:2048
	ds_read_b128 v[220:223], v204 offset:4096
	ds_read_b128 v[224:227], v204 offset:6144
	ds_read_b128 v[228:231], v205 offset:0
	ds_read_b128 v[232:235], v205 offset:2048
	ds_read_b128 v[236:239], v205 offset:4096
	ds_read_b128 v[240:243], v205 offset:6144
	s_add_u32 m0, s76, 0x0
	s_nop 0
	global_load_lds_dwordx4 v196, s[68:69]
	s_add_u32 m0, s76, 0x2000
	s_nop 0
	global_load_lds_dwordx4 v197, s[68:69]
	s_add_u32 m0, s76, 0x4000
	s_nop 0
	global_load_lds_dwordx4 v198, s[68:69]
	s_add_u32 m0, s76, 0x6000
	s_nop 0
	global_load_lds_dwordx4 v199, s[68:69]
	s_add_u32 m0, s76, 0x8000
	s_nop 0
	global_load_lds_dwordx4 v196, s[70:71]
	s_add_u32 m0, s76, 0xa000
	s_nop 0
	global_load_lds_dwordx4 v197, s[70:71]
	s_add_u32 s68, s68, 0x80
	s_addc_u32 s69, s69, 0
	s_add_u32 s70, s70, 0x80
	s_addc_u32 s71, s71, 0
	global_load_dwordx4 v[82:85], v192, s[14:15]
	v_add_u32_e32 v170, s38, v192
	global_load_dwordx4 v[86:89], v170, s[14:15]
	s_waitcnt lgkmcnt(0)
	s_barrier
	v_mfma_f32_16x16x32_bf16 v[2:5], v[146:149], v[130:133], v[2:5]
	v_mfma_f32_16x16x32_bf16 v[6:9], v[150:153], v[130:133], v[6:9]
	v_mfma_f32_16x16x32_bf16 v[10:13], v[154:157], v[130:133], v[10:13]
	v_mfma_f32_16x16x32_bf16 v[14:17], v[158:161], v[130:133], v[14:17]
	v_mfma_f32_16x16x32_bf16 v[18:21], v[146:149], v[134:137], v[18:21]
	v_mfma_f32_16x16x32_bf16 v[22:25], v[150:153], v[134:137], v[22:25]
	v_mfma_f32_16x16x32_bf16 v[26:29], v[154:157], v[134:137], v[26:29]
	v_mfma_f32_16x16x32_bf16 v[30:33], v[158:161], v[134:137], v[30:33]
	v_mfma_f32_16x16x32_bf16 v[34:37], v[146:149], v[138:141], v[34:37]
	v_mfma_f32_16x16x32_bf16 v[38:41], v[150:153], v[138:141], v[38:41]
	v_mfma_f32_16x16x32_bf16 v[42:45], v[154:157], v[138:141], v[42:45]
	v_mfma_f32_16x16x32_bf16 v[46:49], v[158:161], v[138:141], v[46:49]
	v_mfma_f32_16x16x32_bf16 v[50:53], v[146:149], v[142:145], v[50:53]
	v_mfma_f32_16x16x32_bf16 v[54:57], v[150:153], v[142:145], v[54:57]
	v_mfma_f32_16x16x32_bf16 v[58:61], v[154:157], v[142:145], v[58:61]
	v_mfma_f32_16x16x32_bf16 v[62:65], v[158:161], v[142:145], v[62:65]
	v_mfma_f32_16x16x32_bf16 v[2:5], v[228:231], v[212:215], v[2:5]
	v_mfma_f32_16x16x32_bf16 v[6:9], v[232:235], v[212:215], v[6:9]
	v_mfma_f32_16x16x32_bf16 v[10:13], v[236:239], v[212:215], v[10:13]
	v_mfma_f32_16x16x32_bf16 v[14:17], v[240:243], v[212:215], v[14:17]
	v_mfma_f32_16x16x32_bf16 v[18:21], v[228:231], v[216:219], v[18:21]
	v_mfma_f32_16x16x32_bf16 v[22:25], v[232:235], v[216:219], v[22:25]
	v_mfma_f32_16x16x32_bf16 v[26:29], v[236:239], v[216:219], v[26:29]
	v_mfma_f32_16x16x32_bf16 v[30:33], v[240:243], v[216:219], v[30:33]
	v_mfma_f32_16x16x32_bf16 v[34:37], v[228:231], v[220:223], v[34:37]
	v_mfma_f32_16x16x32_bf16 v[38:41], v[232:235], v[220:223], v[38:41]
	v_mfma_f32_16x16x32_bf16 v[42:45], v[236:239], v[220:223], v[42:45]
	v_mfma_f32_16x16x32_bf16 v[46:49], v[240:243], v[220:223], v[46:49]
	v_mfma_f32_16x16x32_bf16 v[50:53], v[228:231], v[224:227], v[50:53]
	v_mfma_f32_16x16x32_bf16 v[54:57], v[232:235], v[224:227], v[54:57]
	v_mfma_f32_16x16x32_bf16 v[58:61], v[236:239], v[224:227], v[58:61]
	v_mfma_f32_16x16x32_bf16 v[62:65], v[240:243], v[224:227], v[62:65]
	s_waitcnt vmcnt(10)
	s_barrier
	v_add_u32_e32 v204, 0x18000, v200
	v_add_u32_e32 v205, 0x18000, v202
	ds_read_b128 v[130:133], v204 offset:0
	ds_read_b128 v[134:137], v204 offset:2048
	ds_read_b128 v[138:141], v204 offset:4096
	ds_read_b128 v[142:145], v204 offset:6144
	ds_read_b128 v[146:149], v205 offset:0
	ds_read_b128 v[150:153], v205 offset:2048
	ds_read_b128 v[154:157], v205 offset:4096
	ds_read_b128 v[158:161], v205 offset:6144
	v_add_u32_e32 v204, 0x18000, v201
	v_add_u32_e32 v205, 0x18000, v203
	ds_read_b128 v[212:215], v204 offset:0
	ds_read_b128 v[216:219], v204 offset:2048
	ds_read_b128 v[220:223], v204 offset:4096
	ds_read_b128 v[224:227], v204 offset:6144
	ds_read_b128 v[228:231], v205 offset:0
	ds_read_b128 v[232:235], v205 offset:2048
	ds_read_b128 v[236:239], v205 offset:4096
	ds_read_b128 v[240:243], v205 offset:6144
	s_add_u32 m0, s76, 0xc000
	s_nop 0
	global_load_lds_dwordx4 v196, s[68:69]
	s_add_u32 m0, s76, 0xe000
	s_nop 0
	global_load_lds_dwordx4 v197, s[68:69]
	s_add_u32 m0, s76, 0x10000
	s_nop 0
	global_load_lds_dwordx4 v198, s[68:69]
	s_add_u32 m0, s76, 0x12000
	s_nop 0
	global_load_lds_dwordx4 v199, s[68:69]
	s_add_u32 m0, s76, 0x14000
	s_nop 0
	global_load_lds_dwordx4 v196, s[70:71]
	s_add_u32 m0, s76, 0x16000
	s_nop 0
	global_load_lds_dwordx4 v197, s[70:71]
	s_add_u32 s68, s68, 0x80
	s_addc_u32 s69, s69, 0
	s_add_u32 s70, s70, 0x80
	s_addc_u32 s71, s71, 0
	v_add_u32_e32 v170, s39, v192
	global_load_dwordx4 v[90:93], v170, s[14:15]
	v_add_u32_e32 v170, s40, v192
	global_load_dwordx4 v[94:97], v170, s[14:15]
	s_waitcnt lgkmcnt(0)
	s_barrier
	v_mfma_f32_16x16x32_bf16 v[2:5], v[146:149], v[130:133], v[2:5]
	v_mfma_f32_16x16x32_bf16 v[6:9], v[150:153], v[130:133], v[6:9]
	v_mfma_f32_16x16x32_bf16 v[10:13], v[154:157], v[130:133], v[10:13]
	v_mfma_f32_16x16x32_bf16 v[14:17], v[158:161], v[130:133], v[14:17]
	v_mfma_f32_16x16x32_bf16 v[18:21], v[146:149], v[134:137], v[18:21]
	v_mfma_f32_16x16x32_bf16 v[22:25], v[150:153], v[134:137], v[22:25]
	v_mfma_f32_16x16x32_bf16 v[26:29], v[154:157], v[134:137], v[26:29]
	v_mfma_f32_16x16x32_bf16 v[30:33], v[158:161], v[134:137], v[30:33]
	v_mfma_f32_16x16x32_bf16 v[34:37], v[146:149], v[138:141], v[34:37]
	v_mfma_f32_16x16x32_bf16 v[38:41], v[150:153], v[138:141], v[38:41]
	v_mfma_f32_16x16x32_bf16 v[42:45], v[154:157], v[138:141], v[42:45]
	v_mfma_f32_16x16x32_bf16 v[46:49], v[158:161], v[138:141], v[46:49]
	v_mfma_f32_16x16x32_bf16 v[50:53], v[146:149], v[142:145], v[50:53]
	v_mfma_f32_16x16x32_bf16 v[54:57], v[150:153], v[142:145], v[54:57]
	v_mfma_f32_16x16x32_bf16 v[58:61], v[154:157], v[142:145], v[58:61]
	v_mfma_f32_16x16x32_bf16 v[62:65], v[158:161], v[142:145], v[62:65]
	v_mfma_f32_16x16x32_bf16 v[2:5], v[228:231], v[212:215], v[2:5]
	v_mfma_f32_16x16x32_bf16 v[6:9], v[232:235], v[212:215], v[6:9]
	v_mfma_f32_16x16x32_bf16 v[10:13], v[236:239], v[212:215], v[10:13]
	v_mfma_f32_16x16x32_bf16 v[14:17], v[240:243], v[212:215], v[14:17]
	v_mfma_f32_16x16x32_bf16 v[18:21], v[228:231], v[216:219], v[18:21]
	v_mfma_f32_16x16x32_bf16 v[22:25], v[232:235], v[216:219], v[22:25]
	v_mfma_f32_16x16x32_bf16 v[26:29], v[236:239], v[216:219], v[26:29]
	v_mfma_f32_16x16x32_bf16 v[30:33], v[240:243], v[216:219], v[30:33]
	v_mfma_f32_16x16x32_bf16 v[34:37], v[228:231], v[220:223], v[34:37]
	v_mfma_f32_16x16x32_bf16 v[38:41], v[232:235], v[220:223], v[38:41]
	v_mfma_f32_16x16x32_bf16 v[42:45], v[236:239], v[220:223], v[42:45]
	v_mfma_f32_16x16x32_bf16 v[46:49], v[240:243], v[220:223], v[46:49]
	v_mfma_f32_16x16x32_bf16 v[50:53], v[228:231], v[224:227], v[50:53]
	v_mfma_f32_16x16x32_bf16 v[54:57], v[232:235], v[224:227], v[54:57]
	v_mfma_f32_16x16x32_bf16 v[58:61], v[236:239], v[224:227], v[58:61]
	v_mfma_f32_16x16x32_bf16 v[62:65], v[240:243], v[224:227], v[62:65]
	s_waitcnt vmcnt(10)
	s_barrier
	v_add_u32_e32 v204, 0x0, v200
	v_add_u32_e32 v205, 0x0, v202
	ds_read_b128 v[130:133], v204 offset:0
	ds_read_b128 v[134:137], v204 offset:2048
	ds_read_b128 v[138:141], v204 offset:4096
	ds_read_b128 v[142:145], v204 offset:6144
	ds_read_b128 v[146:149], v205 offset:0
	ds_read_b128 v[150:153], v205 offset:2048
	ds_read_b128 v[154:157], v205 offset:4096
	ds_read_b128 v[158:161], v205 offset:6144
	v_add_u32_e32 v204, 0x0, v201
	v_add_u32_e32 v205, 0x0, v203
	ds_read_b128 v[212:215], v204 offset:0
	ds_read_b128 v[216:219], v204 offset:2048
	ds_read_b128 v[220:223], v204 offset:4096
	ds_read_b128 v[224:227], v204 offset:6144
	ds_read_b128 v[228:231], v205 offset:0
	ds_read_b128 v[232:235], v205 offset:2048
	ds_read_b128 v[236:239], v205 offset:4096
	ds_read_b128 v[240:243], v205 offset:6144
	s_add_u32 m0, s76, 0x18000
	s_nop 0
	global_load_lds_dwordx4 v196, s[68:69]
	s_add_u32 m0, s76, 0x1a000
	s_nop 0
	global_load_lds_dwordx4 v197, s[68:69]
	s_add_u32 m0, s76, 0x1c000
	s_nop 0
	global_load_lds_dwordx4 v198, s[68:69]
	s_add_u32 m0, s76, 0x1e000
	s_nop 0
	global_load_lds_dwordx4 v199, s[68:69]
	s_add_u32 m0, s76, 0x20000
	s_nop 0
	global_load_lds_dwordx4 v196, s[70:71]
	s_add_u32 m0, s76, 0x22000
	s_nop 0
	global_load_lds_dwordx4 v197, s[70:71]
	s_add_u32 s68, s68, 0x80
	s_addc_u32 s69, s69, 0
	s_add_u32 s70, s70, 0x80
	s_addc_u32 s71, s71, 0
	global_load_dwordx4 v[98:101], v193, s[14:15]
	v_add_u32_e32 v170, s38, v193
	global_load_dwordx4 v[102:105], v170, s[14:15]
	s_waitcnt lgkmcnt(0)
	s_barrier
	v_mfma_f32_16x16x32_bf16 v[2:5], v[146:149], v[130:133], v[2:5]
	v_mfma_f32_16x16x32_bf16 v[6:9], v[150:153], v[130:133], v[6:9]
	v_mfma_f32_16x16x32_bf16 v[10:13], v[154:157], v[130:133], v[10:13]
	v_mfma_f32_16x16x32_bf16 v[14:17], v[158:161], v[130:133], v[14:17]
	v_mfma_f32_16x16x32_bf16 v[18:21], v[146:149], v[134:137], v[18:21]
	v_mfma_f32_16x16x32_bf16 v[22:25], v[150:153], v[134:137], v[22:25]
	v_mfma_f32_16x16x32_bf16 v[26:29], v[154:157], v[134:137], v[26:29]
	v_mfma_f32_16x16x32_bf16 v[30:33], v[158:161], v[134:137], v[30:33]
	v_mfma_f32_16x16x32_bf16 v[34:37], v[146:149], v[138:141], v[34:37]
	v_mfma_f32_16x16x32_bf16 v[38:41], v[150:153], v[138:141], v[38:41]
	v_mfma_f32_16x16x32_bf16 v[42:45], v[154:157], v[138:141], v[42:45]
	v_mfma_f32_16x16x32_bf16 v[46:49], v[158:161], v[138:141], v[46:49]
	v_mfma_f32_16x16x32_bf16 v[50:53], v[146:149], v[142:145], v[50:53]
	v_mfma_f32_16x16x32_bf16 v[54:57], v[150:153], v[142:145], v[54:57]
	v_mfma_f32_16x16x32_bf16 v[58:61], v[154:157], v[142:145], v[58:61]
	v_mfma_f32_16x16x32_bf16 v[62:65], v[158:161], v[142:145], v[62:65]
	v_mfma_f32_16x16x32_bf16 v[2:5], v[228:231], v[212:215], v[2:5]
	v_mfma_f32_16x16x32_bf16 v[6:9], v[232:235], v[212:215], v[6:9]
	v_mfma_f32_16x16x32_bf16 v[10:13], v[236:239], v[212:215], v[10:13]
	v_mfma_f32_16x16x32_bf16 v[14:17], v[240:243], v[212:215], v[14:17]
	v_mfma_f32_16x16x32_bf16 v[18:21], v[228:231], v[216:219], v[18:21]
	v_mfma_f32_16x16x32_bf16 v[22:25], v[232:235], v[216:219], v[22:25]
	v_mfma_f32_16x16x32_bf16 v[26:29], v[236:239], v[216:219], v[26:29]
	v_mfma_f32_16x16x32_bf16 v[30:33], v[240:243], v[216:219], v[30:33]
	v_mfma_f32_16x16x32_bf16 v[34:37], v[228:231], v[220:223], v[34:37]
	v_mfma_f32_16x16x32_bf16 v[38:41], v[232:235], v[220:223], v[38:41]
	v_mfma_f32_16x16x32_bf16 v[42:45], v[236:239], v[220:223], v[42:45]
	v_mfma_f32_16x16x32_bf16 v[46:49], v[240:243], v[220:223], v[46:49]
	v_mfma_f32_16x16x32_bf16 v[50:53], v[228:231], v[224:227], v[50:53]
	v_mfma_f32_16x16x32_bf16 v[54:57], v[232:235], v[224:227], v[54:57]
	v_mfma_f32_16x16x32_bf16 v[58:61], v[236:239], v[224:227], v[58:61]
	v_mfma_f32_16x16x32_bf16 v[62:65], v[240:243], v[224:227], v[62:65]
	s_waitcnt vmcnt(10)
	s_barrier
	v_add_u32_e32 v204, 0xc000, v200
	v_add_u32_e32 v205, 0xc000, v202
	ds_read_b128 v[130:133], v204 offset:0
	ds_read_b128 v[134:137], v204 offset:2048
	ds_read_b128 v[138:141], v204 offset:4096
	ds_read_b128 v[142:145], v204 offset:6144
	ds_read_b128 v[146:149], v205 offset:0
	ds_read_b128 v[150:153], v205 offset:2048
	ds_read_b128 v[154:157], v205 offset:4096
	ds_read_b128 v[158:161], v205 offset:6144
	v_add_u32_e32 v204, 0xc000, v201
	v_add_u32_e32 v205, 0xc000, v203
	ds_read_b128 v[212:215], v204 offset:0
	ds_read_b128 v[216:219], v204 offset:2048
	ds_read_b128 v[220:223], v204 offset:4096
	ds_read_b128 v[224:227], v204 offset:6144
	ds_read_b128 v[228:231], v205 offset:0
	ds_read_b128 v[232:235], v205 offset:2048
	ds_read_b128 v[236:239], v205 offset:4096
	ds_read_b128 v[240:243], v205 offset:6144
	s_add_u32 m0, s76, 0x0
	s_nop 0
	global_load_lds_dwordx4 v196, s[68:69]
	s_add_u32 m0, s76, 0x2000
	s_nop 0
	global_load_lds_dwordx4 v197, s[68:69]
	s_add_u32 m0, s76, 0x4000
	s_nop 0
	global_load_lds_dwordx4 v198, s[68:69]
	s_add_u32 m0, s76, 0x6000
	s_nop 0
	global_load_lds_dwordx4 v199, s[68:69]
	s_add_u32 m0, s76, 0x8000
	s_nop 0
	global_load_lds_dwordx4 v196, s[70:71]
	s_add_u32 m0, s76, 0xa000
	s_nop 0
	global_load_lds_dwordx4 v197, s[70:71]
	s_add_u32 s68, s68, 0x80
	s_addc_u32 s69, s69, 0
	s_add_u32 s70, s70, 0x80
	s_addc_u32 s71, s71, 0
	v_add_u32_e32 v170, s39, v193
	global_load_dwordx4 v[106:109], v170, s[14:15]
	v_add_u32_e32 v170, s40, v193
	global_load_dwordx4 v[110:113], v170, s[14:15]
	s_waitcnt lgkmcnt(0)
	s_barrier
	v_mfma_f32_16x16x32_bf16 v[2:5], v[146:149], v[130:133], v[2:5]
	v_mfma_f32_16x16x32_bf16 v[6:9], v[150:153], v[130:133], v[6:9]
	v_mfma_f32_16x16x32_bf16 v[10:13], v[154:157], v[130:133], v[10:13]
	v_mfma_f32_16x16x32_bf16 v[14:17], v[158:161], v[130:133], v[14:17]
	v_mfma_f32_16x16x32_bf16 v[18:21], v[146:149], v[134:137], v[18:21]
	v_mfma_f32_16x16x32_bf16 v[22:25], v[150:153], v[134:137], v[22:25]
	v_mfma_f32_16x16x32_bf16 v[26:29], v[154:157], v[134:137], v[26:29]
	v_mfma_f32_16x16x32_bf16 v[30:33], v[158:161], v[134:137], v[30:33]
	v_mfma_f32_16x16x32_bf16 v[34:37], v[146:149], v[138:141], v[34:37]
	v_mfma_f32_16x16x32_bf16 v[38:41], v[150:153], v[138:141], v[38:41]
	v_mfma_f32_16x16x32_bf16 v[42:45], v[154:157], v[138:141], v[42:45]
	v_mfma_f32_16x16x32_bf16 v[46:49], v[158:161], v[138:141], v[46:49]
	v_mfma_f32_16x16x32_bf16 v[50:53], v[146:149], v[142:145], v[50:53]
	v_mfma_f32_16x16x32_bf16 v[54:57], v[150:153], v[142:145], v[54:57]
	v_mfma_f32_16x16x32_bf16 v[58:61], v[154:157], v[142:145], v[58:61]
	v_mfma_f32_16x16x32_bf16 v[62:65], v[158:161], v[142:145], v[62:65]
	v_mfma_f32_16x16x32_bf16 v[2:5], v[228:231], v[212:215], v[2:5]
	v_mfma_f32_16x16x32_bf16 v[6:9], v[232:235], v[212:215], v[6:9]
	v_mfma_f32_16x16x32_bf16 v[10:13], v[236:239], v[212:215], v[10:13]
	v_mfma_f32_16x16x32_bf16 v[14:17], v[240:243], v[212:215], v[14:17]
	v_mfma_f32_16x16x32_bf16 v[18:21], v[228:231], v[216:219], v[18:21]
	v_mfma_f32_16x16x32_bf16 v[22:25], v[232:235], v[216:219], v[22:25]
	v_mfma_f32_16x16x32_bf16 v[26:29], v[236:239], v[216:219], v[26:29]
	v_mfma_f32_16x16x32_bf16 v[30:33], v[240:243], v[216:219], v[30:33]
	v_mfma_f32_16x16x32_bf16 v[34:37], v[228:231], v[220:223], v[34:37]
	v_mfma_f32_16x16x32_bf16 v[38:41], v[232:235], v[220:223], v[38:41]
	v_mfma_f32_16x16x32_bf16 v[42:45], v[236:239], v[220:223], v[42:45]
	v_mfma_f32_16x16x32_bf16 v[46:49], v[240:243], v[220:223], v[46:49]
	v_mfma_f32_16x16x32_bf16 v[50:53], v[228:231], v[224:227], v[50:53]
	v_mfma_f32_16x16x32_bf16 v[54:57], v[232:235], v[224:227], v[54:57]
	v_mfma_f32_16x16x32_bf16 v[58:61], v[236:239], v[224:227], v[58:61]
	v_mfma_f32_16x16x32_bf16 v[62:65], v[240:243], v[224:227], v[62:65]
	s_waitcnt vmcnt(10)
	s_barrier
	v_add_u32_e32 v204, 0x18000, v200
	v_add_u32_e32 v205, 0x18000, v202
	ds_read_b128 v[130:133], v204 offset:0
	ds_read_b128 v[134:137], v204 offset:2048
	ds_read_b128 v[138:141], v204 offset:4096
	ds_read_b128 v[142:145], v204 offset:6144
	ds_read_b128 v[146:149], v205 offset:0
	ds_read_b128 v[150:153], v205 offset:2048
	ds_read_b128 v[154:157], v205 offset:4096
	ds_read_b128 v[158:161], v205 offset:6144
	v_add_u32_e32 v204, 0x18000, v201
	v_add_u32_e32 v205, 0x18000, v203
	ds_read_b128 v[212:215], v204 offset:0
	ds_read_b128 v[216:219], v204 offset:2048
	ds_read_b128 v[220:223], v204 offset:4096
	ds_read_b128 v[224:227], v204 offset:6144
	ds_read_b128 v[228:231], v205 offset:0
	ds_read_b128 v[232:235], v205 offset:2048
	ds_read_b128 v[236:239], v205 offset:4096
	ds_read_b128 v[240:243], v205 offset:6144
	s_add_u32 m0, s76, 0xc000
	s_nop 0
	global_load_lds_dwordx4 v196, s[68:69]
	s_add_u32 m0, s76, 0xe000
	s_nop 0
	global_load_lds_dwordx4 v197, s[68:69]
	s_add_u32 m0, s76, 0x10000
	s_nop 0
	global_load_lds_dwordx4 v198, s[68:69]
	s_add_u32 m0, s76, 0x12000
	s_nop 0
	global_load_lds_dwordx4 v199, s[68:69]
	s_add_u32 m0, s76, 0x14000
	s_nop 0
	global_load_lds_dwordx4 v196, s[70:71]
	s_add_u32 m0, s76, 0x16000
	s_nop 0
	global_load_lds_dwordx4 v197, s[70:71]
	s_add_u32 s68, s68, 0x80
	s_addc_u32 s69, s69, 0
	s_add_u32 s70, s70, 0x80
	s_addc_u32 s71, s71, 0
	global_load_dwordx4 v[114:117], v244, s[14:15]
	v_add_u32_e32 v170, s38, v244
	global_load_dwordx4 v[118:121], v170, s[14:15]
	s_waitcnt lgkmcnt(0)
	s_barrier
	v_mfma_f32_16x16x32_bf16 v[2:5], v[146:149], v[130:133], v[2:5]
	v_mfma_f32_16x16x32_bf16 v[6:9], v[150:153], v[130:133], v[6:9]
	v_mfma_f32_16x16x32_bf16 v[10:13], v[154:157], v[130:133], v[10:13]
	v_mfma_f32_16x16x32_bf16 v[14:17], v[158:161], v[130:133], v[14:17]
	v_mfma_f32_16x16x32_bf16 v[18:21], v[146:149], v[134:137], v[18:21]
	v_mfma_f32_16x16x32_bf16 v[22:25], v[150:153], v[134:137], v[22:25]
	v_mfma_f32_16x16x32_bf16 v[26:29], v[154:157], v[134:137], v[26:29]
	v_mfma_f32_16x16x32_bf16 v[30:33], v[158:161], v[134:137], v[30:33]
	v_mfma_f32_16x16x32_bf16 v[34:37], v[146:149], v[138:141], v[34:37]
	v_mfma_f32_16x16x32_bf16 v[38:41], v[150:153], v[138:141], v[38:41]
	v_mfma_f32_16x16x32_bf16 v[42:45], v[154:157], v[138:141], v[42:45]
	v_mfma_f32_16x16x32_bf16 v[46:49], v[158:161], v[138:141], v[46:49]
	v_mfma_f32_16x16x32_bf16 v[50:53], v[146:149], v[142:145], v[50:53]
	v_mfma_f32_16x16x32_bf16 v[54:57], v[150:153], v[142:145], v[54:57]
	v_mfma_f32_16x16x32_bf16 v[58:61], v[154:157], v[142:145], v[58:61]
	v_mfma_f32_16x16x32_bf16 v[62:65], v[158:161], v[142:145], v[62:65]
	v_mfma_f32_16x16x32_bf16 v[2:5], v[228:231], v[212:215], v[2:5]
	v_mfma_f32_16x16x32_bf16 v[6:9], v[232:235], v[212:215], v[6:9]
	v_mfma_f32_16x16x32_bf16 v[10:13], v[236:239], v[212:215], v[10:13]
	v_mfma_f32_16x16x32_bf16 v[14:17], v[240:243], v[212:215], v[14:17]
	v_mfma_f32_16x16x32_bf16 v[18:21], v[228:231], v[216:219], v[18:21]
	v_mfma_f32_16x16x32_bf16 v[22:25], v[232:235], v[216:219], v[22:25]
	v_mfma_f32_16x16x32_bf16 v[26:29], v[236:239], v[216:219], v[26:29]
	v_mfma_f32_16x16x32_bf16 v[30:33], v[240:243], v[216:219], v[30:33]
	v_mfma_f32_16x16x32_bf16 v[34:37], v[228:231], v[220:223], v[34:37]
	v_mfma_f32_16x16x32_bf16 v[38:41], v[232:235], v[220:223], v[38:41]
	v_mfma_f32_16x16x32_bf16 v[42:45], v[236:239], v[220:223], v[42:45]
	v_mfma_f32_16x16x32_bf16 v[46:49], v[240:243], v[220:223], v[46:49]
	v_mfma_f32_16x16x32_bf16 v[50:53], v[228:231], v[224:227], v[50:53]
	v_mfma_f32_16x16x32_bf16 v[54:57], v[232:235], v[224:227], v[54:57]
	v_mfma_f32_16x16x32_bf16 v[58:61], v[236:239], v[224:227], v[58:61]
	v_mfma_f32_16x16x32_bf16 v[62:65], v[240:243], v[224:227], v[62:65]
	s_waitcnt vmcnt(10)
	s_barrier
	v_add_u32_e32 v204, 0x0, v200
	v_add_u32_e32 v205, 0x0, v202
	ds_read_b128 v[130:133], v204 offset:0
	ds_read_b128 v[134:137], v204 offset:2048
	ds_read_b128 v[138:141], v204 offset:4096
	ds_read_b128 v[142:145], v204 offset:6144
	ds_read_b128 v[146:149], v205 offset:0
	ds_read_b128 v[150:153], v205 offset:2048
	ds_read_b128 v[154:157], v205 offset:4096
	ds_read_b128 v[158:161], v205 offset:6144
	v_add_u32_e32 v204, 0x0, v201
	v_add_u32_e32 v205, 0x0, v203
	ds_read_b128 v[212:215], v204 offset:0
	ds_read_b128 v[216:219], v204 offset:2048
	ds_read_b128 v[220:223], v204 offset:4096
	ds_read_b128 v[224:227], v204 offset:6144
	ds_read_b128 v[228:231], v205 offset:0
	ds_read_b128 v[232:235], v205 offset:2048
	ds_read_b128 v[236:239], v205 offset:4096
	ds_read_b128 v[240:243], v205 offset:6144
	s_add_u32 m0, s76, 0x18000
	s_nop 0
	global_load_lds_dwordx4 v196, s[68:69]
	s_add_u32 m0, s76, 0x1a000
	s_nop 0
	global_load_lds_dwordx4 v197, s[68:69]
	s_add_u32 m0, s76, 0x1c000
	s_nop 0
	global_load_lds_dwordx4 v198, s[68:69]
	s_add_u32 m0, s76, 0x1e000
	s_nop 0
	global_load_lds_dwordx4 v199, s[68:69]
	s_add_u32 m0, s76, 0x20000
	s_nop 0
	global_load_lds_dwordx4 v196, s[70:71]
	s_add_u32 m0, s76, 0x22000
	s_nop 0
	global_load_lds_dwordx4 v197, s[70:71]
	s_add_u32 s68, s68, 0x80
	s_addc_u32 s69, s69, 0
	s_add_u32 s70, s70, 0x80
	s_addc_u32 s71, s71, 0
	v_add_u32_e32 v170, s39, v244
	global_load_dwordx4 v[122:125], v170, s[14:15]
	v_add_u32_e32 v170, s40, v244
	global_load_dwordx4 v[126:129], v170, s[14:15]
	s_waitcnt lgkmcnt(0)
	s_barrier
	v_mfma_f32_16x16x32_bf16 v[2:5], v[146:149], v[130:133], v[2:5]
	v_mfma_f32_16x16x32_bf16 v[6:9], v[150:153], v[130:133], v[6:9]
	v_mfma_f32_16x16x32_bf16 v[10:13], v[154:157], v[130:133], v[10:13]
	v_mfma_f32_16x16x32_bf16 v[14:17], v[158:161], v[130:133], v[14:17]
	v_mfma_f32_16x16x32_bf16 v[18:21], v[146:149], v[134:137], v[18:21]
	v_mfma_f32_16x16x32_bf16 v[22:25], v[150:153], v[134:137], v[22:25]
	v_mfma_f32_16x16x32_bf16 v[26:29], v[154:157], v[134:137], v[26:29]
	v_mfma_f32_16x16x32_bf16 v[30:33], v[158:161], v[134:137], v[30:33]
	v_mfma_f32_16x16x32_bf16 v[34:37], v[146:149], v[138:141], v[34:37]
	v_mfma_f32_16x16x32_bf16 v[38:41], v[150:153], v[138:141], v[38:41]
	v_mfma_f32_16x16x32_bf16 v[42:45], v[154:157], v[138:141], v[42:45]
	v_mfma_f32_16x16x32_bf16 v[46:49], v[158:161], v[138:141], v[46:49]
	v_mfma_f32_16x16x32_bf16 v[50:53], v[146:149], v[142:145], v[50:53]
	v_mfma_f32_16x16x32_bf16 v[54:57], v[150:153], v[142:145], v[54:57]
	v_mfma_f32_16x16x32_bf16 v[58:61], v[154:157], v[142:145], v[58:61]
	v_mfma_f32_16x16x32_bf16 v[62:65], v[158:161], v[142:145], v[62:65]
	v_mfma_f32_16x16x32_bf16 v[2:5], v[228:231], v[212:215], v[2:5]
	v_mfma_f32_16x16x32_bf16 v[6:9], v[232:235], v[212:215], v[6:9]
	v_mfma_f32_16x16x32_bf16 v[10:13], v[236:239], v[212:215], v[10:13]
	v_mfma_f32_16x16x32_bf16 v[14:17], v[240:243], v[212:215], v[14:17]
	v_mfma_f32_16x16x32_bf16 v[18:21], v[228:231], v[216:219], v[18:21]
	v_mfma_f32_16x16x32_bf16 v[22:25], v[232:235], v[216:219], v[22:25]
	v_mfma_f32_16x16x32_bf16 v[26:29], v[236:239], v[216:219], v[26:29]
	v_mfma_f32_16x16x32_bf16 v[30:33], v[240:243], v[216:219], v[30:33]
	v_mfma_f32_16x16x32_bf16 v[34:37], v[228:231], v[220:223], v[34:37]
	v_mfma_f32_16x16x32_bf16 v[38:41], v[232:235], v[220:223], v[38:41]
	v_mfma_f32_16x16x32_bf16 v[42:45], v[236:239], v[220:223], v[42:45]
	v_mfma_f32_16x16x32_bf16 v[46:49], v[240:243], v[220:223], v[46:49]
	v_mfma_f32_16x16x32_bf16 v[50:53], v[228:231], v[224:227], v[50:53]
	v_mfma_f32_16x16x32_bf16 v[54:57], v[232:235], v[224:227], v[54:57]
	v_mfma_f32_16x16x32_bf16 v[58:61], v[236:239], v[224:227], v[58:61]
	v_mfma_f32_16x16x32_bf16 v[62:65], v[240:243], v[224:227], v[62:65]
	s_waitcnt vmcnt(10)
	s_barrier
	v_add_u32_e32 v204, 0xc000, v200
	v_add_u32_e32 v205, 0xc000, v202
	ds_read_b128 v[130:133], v204 offset:0
	ds_read_b128 v[134:137], v204 offset:2048
	ds_read_b128 v[138:141], v204 offset:4096
	ds_read_b128 v[142:145], v204 offset:6144
	ds_read_b128 v[146:149], v205 offset:0
	ds_read_b128 v[150:153], v205 offset:2048
	ds_read_b128 v[154:157], v205 offset:4096
	ds_read_b128 v[158:161], v205 offset:6144
	v_add_u32_e32 v204, 0xc000, v201
	v_add_u32_e32 v205, 0xc000, v203
	ds_read_b128 v[212:215], v204 offset:0
	ds_read_b128 v[216:219], v204 offset:2048
	ds_read_b128 v[220:223], v204 offset:4096
	ds_read_b128 v[224:227], v204 offset:6144
	ds_read_b128 v[228:231], v205 offset:0
	ds_read_b128 v[232:235], v205 offset:2048
	ds_read_b128 v[236:239], v205 offset:4096
	ds_read_b128 v[240:243], v205 offset:6144
	s_add_u32 m0, s76, 0x0
	s_nop 0
	global_load_lds_dwordx4 v196, s[68:69]
	s_add_u32 m0, s76, 0x2000
	s_nop 0
	global_load_lds_dwordx4 v197, s[68:69]
	s_add_u32 m0, s76, 0x4000
	s_nop 0
	global_load_lds_dwordx4 v198, s[68:69]
	s_add_u32 m0, s76, 0x6000
	s_nop 0
	global_load_lds_dwordx4 v199, s[68:69]
	s_add_u32 m0, s76, 0x8000
	s_nop 0
	global_load_lds_dwordx4 v196, s[70:71]
	s_add_u32 m0, s76, 0xa000
	s_nop 0
	global_load_lds_dwordx4 v197, s[70:71]
	s_add_u32 s68, s68, 0x80
	s_addc_u32 s69, s69, 0
	s_add_u32 s70, s70, 0x80
	s_addc_u32 s71, s71, 0
	s_waitcnt lgkmcnt(0)
	s_barrier
	v_mfma_f32_16x16x32_bf16 v[2:5], v[146:149], v[130:133], v[2:5]
	v_mfma_f32_16x16x32_bf16 v[6:9], v[150:153], v[130:133], v[6:9]
	v_mfma_f32_16x16x32_bf16 v[10:13], v[154:157], v[130:133], v[10:13]
	v_mfma_f32_16x16x32_bf16 v[14:17], v[158:161], v[130:133], v[14:17]
	v_mfma_f32_16x16x32_bf16 v[18:21], v[146:149], v[134:137], v[18:21]
	v_mfma_f32_16x16x32_bf16 v[22:25], v[150:153], v[134:137], v[22:25]
	v_mfma_f32_16x16x32_bf16 v[26:29], v[154:157], v[134:137], v[26:29]
	v_mfma_f32_16x16x32_bf16 v[30:33], v[158:161], v[134:137], v[30:33]
	v_mfma_f32_16x16x32_bf16 v[34:37], v[146:149], v[138:141], v[34:37]
	v_mfma_f32_16x16x32_bf16 v[38:41], v[150:153], v[138:141], v[38:41]
	v_mfma_f32_16x16x32_bf16 v[42:45], v[154:157], v[138:141], v[42:45]
	v_mfma_f32_16x16x32_bf16 v[46:49], v[158:161], v[138:141], v[46:49]
	v_mfma_f32_16x16x32_bf16 v[50:53], v[146:149], v[142:145], v[50:53]
	v_mfma_f32_16x16x32_bf16 v[54:57], v[150:153], v[142:145], v[54:57]
	v_mfma_f32_16x16x32_bf16 v[58:61], v[154:157], v[142:145], v[58:61]
	v_mfma_f32_16x16x32_bf16 v[62:65], v[158:161], v[142:145], v[62:65]
	v_mfma_f32_16x16x32_bf16 v[2:5], v[228:231], v[212:215], v[2:5]
	v_mfma_f32_16x16x32_bf16 v[6:9], v[232:235], v[212:215], v[6:9]
	v_mfma_f32_16x16x32_bf16 v[10:13], v[236:239], v[212:215], v[10:13]
	v_mfma_f32_16x16x32_bf16 v[14:17], v[240:243], v[212:215], v[14:17]
	v_mfma_f32_16x16x32_bf16 v[18:21], v[228:231], v[216:219], v[18:21]
	v_mfma_f32_16x16x32_bf16 v[22:25], v[232:235], v[216:219], v[22:25]
	v_mfma_f32_16x16x32_bf16 v[26:29], v[236:239], v[216:219], v[26:29]
	v_mfma_f32_16x16x32_bf16 v[30:33], v[240:243], v[216:219], v[30:33]
	v_mfma_f32_16x16x32_bf16 v[34:37], v[228:231], v[220:223], v[34:37]
	v_mfma_f32_16x16x32_bf16 v[38:41], v[232:235], v[220:223], v[38:41]
	v_mfma_f32_16x16x32_bf16 v[42:45], v[236:239], v[220:223], v[42:45]
	v_mfma_f32_16x16x32_bf16 v[46:49], v[240:243], v[220:223], v[46:49]
	v_mfma_f32_16x16x32_bf16 v[50:53], v[228:231], v[224:227], v[50:53]
	v_mfma_f32_16x16x32_bf16 v[54:57], v[232:235], v[224:227], v[54:57]
	v_mfma_f32_16x16x32_bf16 v[58:61], v[236:239], v[224:227], v[58:61]
	v_mfma_f32_16x16x32_bf16 v[62:65], v[240:243], v[224:227], v[62:65]
	s_waitcnt vmcnt(8)
	s_barrier
	v_add_u32_e32 v204, 0x18000, v200
	v_add_u32_e32 v205, 0x18000, v202
	ds_read_b128 v[130:133], v204 offset:0
	ds_read_b128 v[134:137], v204 offset:2048
	ds_read_b128 v[138:141], v204 offset:4096
	ds_read_b128 v[142:145], v204 offset:6144
	ds_read_b128 v[146:149], v205 offset:0
	ds_read_b128 v[150:153], v205 offset:2048
	ds_read_b128 v[154:157], v205 offset:4096
	ds_read_b128 v[158:161], v205 offset:6144
	v_add_u32_e32 v204, 0x18000, v201
	v_add_u32_e32 v205, 0x18000, v203
	ds_read_b128 v[212:215], v204 offset:0
	ds_read_b128 v[216:219], v204 offset:2048
	ds_read_b128 v[220:223], v204 offset:4096
	ds_read_b128 v[224:227], v204 offset:6144
	ds_read_b128 v[228:231], v205 offset:0
	ds_read_b128 v[232:235], v205 offset:2048
	ds_read_b128 v[236:239], v205 offset:4096
	ds_read_b128 v[240:243], v205 offset:6144
	s_add_u32 m0, s76, 0xc000
	s_nop 0
	global_load_lds_dwordx4 v196, s[68:69]
	s_add_u32 m0, s76, 0xe000
	s_nop 0
	global_load_lds_dwordx4 v197, s[68:69]
	s_add_u32 m0, s76, 0x10000
	s_nop 0
	global_load_lds_dwordx4 v198, s[68:69]
	s_add_u32 m0, s76, 0x12000
	s_nop 0
	global_load_lds_dwordx4 v199, s[68:69]
	s_add_u32 m0, s76, 0x14000
	s_nop 0
	global_load_lds_dwordx4 v196, s[70:71]
	s_add_u32 m0, s76, 0x16000
	s_nop 0
	global_load_lds_dwordx4 v197, s[70:71]
	s_add_u32 s68, s68, 0x80
	s_addc_u32 s69, s69, 0
	s_add_u32 s70, s70, 0x80
	s_addc_u32 s71, s71, 0
	s_waitcnt lgkmcnt(0)
	s_barrier
	v_mfma_f32_16x16x32_bf16 v[2:5], v[146:149], v[130:133], v[2:5]
	v_mfma_f32_16x16x32_bf16 v[6:9], v[150:153], v[130:133], v[6:9]
	v_mfma_f32_16x16x32_bf16 v[10:13], v[154:157], v[130:133], v[10:13]
	v_mfma_f32_16x16x32_bf16 v[14:17], v[158:161], v[130:133], v[14:17]
	v_mfma_f32_16x16x32_bf16 v[18:21], v[146:149], v[134:137], v[18:21]
	v_mfma_f32_16x16x32_bf16 v[22:25], v[150:153], v[134:137], v[22:25]
	v_mfma_f32_16x16x32_bf16 v[26:29], v[154:157], v[134:137], v[26:29]
	v_mfma_f32_16x16x32_bf16 v[30:33], v[158:161], v[134:137], v[30:33]
	v_mfma_f32_16x16x32_bf16 v[34:37], v[146:149], v[138:141], v[34:37]
	v_mfma_f32_16x16x32_bf16 v[38:41], v[150:153], v[138:141], v[38:41]
	v_mfma_f32_16x16x32_bf16 v[42:45], v[154:157], v[138:141], v[42:45]
	v_mfma_f32_16x16x32_bf16 v[46:49], v[158:161], v[138:141], v[46:49]
	v_mfma_f32_16x16x32_bf16 v[50:53], v[146:149], v[142:145], v[50:53]
	v_mfma_f32_16x16x32_bf16 v[54:57], v[150:153], v[142:145], v[54:57]
	v_mfma_f32_16x16x32_bf16 v[58:61], v[154:157], v[142:145], v[58:61]
	v_mfma_f32_16x16x32_bf16 v[62:65], v[158:161], v[142:145], v[62:65]
	v_mfma_f32_16x16x32_bf16 v[2:5], v[228:231], v[212:215], v[2:5]
	v_mfma_f32_16x16x32_bf16 v[6:9], v[232:235], v[212:215], v[6:9]
	v_mfma_f32_16x16x32_bf16 v[10:13], v[236:239], v[212:215], v[10:13]
	v_mfma_f32_16x16x32_bf16 v[14:17], v[240:243], v[212:215], v[14:17]
	v_mfma_f32_16x16x32_bf16 v[18:21], v[228:231], v[216:219], v[18:21]
	v_mfma_f32_16x16x32_bf16 v[22:25], v[232:235], v[216:219], v[22:25]
	v_mfma_f32_16x16x32_bf16 v[26:29], v[236:239], v[216:219], v[26:29]
	v_mfma_f32_16x16x32_bf16 v[30:33], v[240:243], v[216:219], v[30:33]
	v_mfma_f32_16x16x32_bf16 v[34:37], v[228:231], v[220:223], v[34:37]
	v_mfma_f32_16x16x32_bf16 v[38:41], v[232:235], v[220:223], v[38:41]
	v_mfma_f32_16x16x32_bf16 v[42:45], v[236:239], v[220:223], v[42:45]
	v_mfma_f32_16x16x32_bf16 v[46:49], v[240:243], v[220:223], v[46:49]
	v_mfma_f32_16x16x32_bf16 v[50:53], v[228:231], v[224:227], v[50:53]
	v_mfma_f32_16x16x32_bf16 v[54:57], v[232:235], v[224:227], v[54:57]
	v_mfma_f32_16x16x32_bf16 v[58:61], v[236:239], v[224:227], v[58:61]
	v_mfma_f32_16x16x32_bf16 v[62:65], v[240:243], v[224:227], v[62:65]
	s_waitcnt vmcnt(6)
	s_barrier
	v_add_u32_e32 v204, 0x0, v200
	v_add_u32_e32 v205, 0x0, v202
	ds_read_b128 v[130:133], v204 offset:0
	ds_read_b128 v[134:137], v204 offset:2048
	ds_read_b128 v[138:141], v204 offset:4096
	ds_read_b128 v[142:145], v204 offset:6144
	ds_read_b128 v[146:149], v205 offset:0
	ds_read_b128 v[150:153], v205 offset:2048
	ds_read_b128 v[154:157], v205 offset:4096
	ds_read_b128 v[158:161], v205 offset:6144
	v_add_u32_e32 v204, 0x0, v201
	v_add_u32_e32 v205, 0x0, v203
	ds_read_b128 v[212:215], v204 offset:0
	ds_read_b128 v[216:219], v204 offset:2048
	ds_read_b128 v[220:223], v204 offset:4096
	ds_read_b128 v[224:227], v204 offset:6144
	ds_read_b128 v[228:231], v205 offset:0
	ds_read_b128 v[232:235], v205 offset:2048
	ds_read_b128 v[236:239], v205 offset:4096
	ds_read_b128 v[240:243], v205 offset:6144
	s_add_u32 m0, s76, 0x18000
	s_nop 0
	global_load_lds_dwordx4 v196, s[68:69]
	s_add_u32 m0, s76, 0x1a000
	s_nop 0
	global_load_lds_dwordx4 v197, s[68:69]
	s_add_u32 m0, s76, 0x1c000
	s_nop 0
	global_load_lds_dwordx4 v198, s[68:69]
	s_add_u32 m0, s76, 0x1e000
	s_nop 0
	global_load_lds_dwordx4 v199, s[68:69]
	s_add_u32 m0, s76, 0x20000
	s_nop 0
	global_load_lds_dwordx4 v196, s[70:71]
	s_add_u32 m0, s76, 0x22000
	s_nop 0
	global_load_lds_dwordx4 v197, s[70:71]
	s_add_u32 s68, s68, 0x80
	s_addc_u32 s69, s69, 0
	s_add_u32 s70, s70, 0x80
	s_addc_u32 s71, s71, 0
	s_waitcnt lgkmcnt(0)
	s_barrier
	v_mfma_f32_16x16x32_bf16 v[2:5], v[146:149], v[130:133], v[2:5]
	v_mfma_f32_16x16x32_bf16 v[6:9], v[150:153], v[130:133], v[6:9]
	v_mfma_f32_16x16x32_bf16 v[10:13], v[154:157], v[130:133], v[10:13]
	v_mfma_f32_16x16x32_bf16 v[14:17], v[158:161], v[130:133], v[14:17]
	v_mfma_f32_16x16x32_bf16 v[18:21], v[146:149], v[134:137], v[18:21]
	v_mfma_f32_16x16x32_bf16 v[22:25], v[150:153], v[134:137], v[22:25]
	v_mfma_f32_16x16x32_bf16 v[26:29], v[154:157], v[134:137], v[26:29]
	v_mfma_f32_16x16x32_bf16 v[30:33], v[158:161], v[134:137], v[30:33]
	v_mfma_f32_16x16x32_bf16 v[34:37], v[146:149], v[138:141], v[34:37]
	v_mfma_f32_16x16x32_bf16 v[38:41], v[150:153], v[138:141], v[38:41]
	v_mfma_f32_16x16x32_bf16 v[42:45], v[154:157], v[138:141], v[42:45]
	v_mfma_f32_16x16x32_bf16 v[46:49], v[158:161], v[138:141], v[46:49]
	v_mfma_f32_16x16x32_bf16 v[50:53], v[146:149], v[142:145], v[50:53]
	v_mfma_f32_16x16x32_bf16 v[54:57], v[150:153], v[142:145], v[54:57]
	v_mfma_f32_16x16x32_bf16 v[58:61], v[154:157], v[142:145], v[58:61]
	v_mfma_f32_16x16x32_bf16 v[62:65], v[158:161], v[142:145], v[62:65]
	v_mfma_f32_16x16x32_bf16 v[2:5], v[228:231], v[212:215], v[2:5]
	v_mfma_f32_16x16x32_bf16 v[6:9], v[232:235], v[212:215], v[6:9]
	v_mfma_f32_16x16x32_bf16 v[10:13], v[236:239], v[212:215], v[10:13]
	v_mfma_f32_16x16x32_bf16 v[14:17], v[240:243], v[212:215], v[14:17]
	v_mfma_f32_16x16x32_bf16 v[18:21], v[228:231], v[216:219], v[18:21]
	v_mfma_f32_16x16x32_bf16 v[22:25], v[232:235], v[216:219], v[22:25]
	v_mfma_f32_16x16x32_bf16 v[26:29], v[236:239], v[216:219], v[26:29]
	v_mfma_f32_16x16x32_bf16 v[30:33], v[240:243], v[216:219], v[30:33]
	v_mfma_f32_16x16x32_bf16 v[34:37], v[228:231], v[220:223], v[34:37]
	v_mfma_f32_16x16x32_bf16 v[38:41], v[232:235], v[220:223], v[38:41]
	v_mfma_f32_16x16x32_bf16 v[42:45], v[236:239], v[220:223], v[42:45]
	v_mfma_f32_16x16x32_bf16 v[46:49], v[240:243], v[220:223], v[46:49]
	v_mfma_f32_16x16x32_bf16 v[50:53], v[228:231], v[224:227], v[50:53]
	v_mfma_f32_16x16x32_bf16 v[54:57], v[232:235], v[224:227], v[54:57]
	v_mfma_f32_16x16x32_bf16 v[58:61], v[236:239], v[224:227], v[58:61]
	v_mfma_f32_16x16x32_bf16 v[62:65], v[240:243], v[224:227], v[62:65]
	s_waitcnt vmcnt(6)
	s_barrier
	v_add_u32_e32 v204, 0xc000, v200
	v_add_u32_e32 v205, 0xc000, v202
	ds_read_b128 v[130:133], v204 offset:0
	ds_read_b128 v[134:137], v204 offset:2048
	ds_read_b128 v[138:141], v204 offset:4096
	ds_read_b128 v[142:145], v204 offset:6144
	ds_read_b128 v[146:149], v205 offset:0
	ds_read_b128 v[150:153], v205 offset:2048
	ds_read_b128 v[154:157], v205 offset:4096
	ds_read_b128 v[158:161], v205 offset:6144
	v_add_u32_e32 v204, 0xc000, v201
	v_add_u32_e32 v205, 0xc000, v203
	ds_read_b128 v[212:215], v204 offset:0
	ds_read_b128 v[216:219], v204 offset:2048
	ds_read_b128 v[220:223], v204 offset:4096
	ds_read_b128 v[224:227], v204 offset:6144
	ds_read_b128 v[228:231], v205 offset:0
	ds_read_b128 v[232:235], v205 offset:2048
	ds_read_b128 v[236:239], v205 offset:4096
	ds_read_b128 v[240:243], v205 offset:6144
	s_add_u32 m0, s76, 0x0
	s_nop 0
	global_load_lds_dwordx4 v196, s[68:69]
	s_add_u32 m0, s76, 0x2000
	s_nop 0
	global_load_lds_dwordx4 v197, s[68:69]
	s_add_u32 m0, s76, 0x4000
	s_nop 0
	global_load_lds_dwordx4 v198, s[68:69]
	s_add_u32 m0, s76, 0x6000
	s_nop 0
	global_load_lds_dwordx4 v199, s[68:69]
	s_add_u32 m0, s76, 0x8000
	s_nop 0
	global_load_lds_dwordx4 v196, s[70:71]
	s_add_u32 m0, s76, 0xa000
	s_nop 0
	global_load_lds_dwordx4 v197, s[70:71]
	s_add_u32 s68, s68, 0x80
	s_addc_u32 s69, s69, 0
	s_add_u32 s70, s70, 0x80
	s_addc_u32 s71, s71, 0
	s_waitcnt lgkmcnt(0)
	s_barrier
	v_mfma_f32_16x16x32_bf16 v[2:5], v[146:149], v[130:133], v[2:5]
	v_mfma_f32_16x16x32_bf16 v[6:9], v[150:153], v[130:133], v[6:9]
	v_mfma_f32_16x16x32_bf16 v[10:13], v[154:157], v[130:133], v[10:13]
	v_mfma_f32_16x16x32_bf16 v[14:17], v[158:161], v[130:133], v[14:17]
	v_mfma_f32_16x16x32_bf16 v[18:21], v[146:149], v[134:137], v[18:21]
	v_mfma_f32_16x16x32_bf16 v[22:25], v[150:153], v[134:137], v[22:25]
	v_mfma_f32_16x16x32_bf16 v[26:29], v[154:157], v[134:137], v[26:29]
	v_mfma_f32_16x16x32_bf16 v[30:33], v[158:161], v[134:137], v[30:33]
	v_mfma_f32_16x16x32_bf16 v[34:37], v[146:149], v[138:141], v[34:37]
	v_mfma_f32_16x16x32_bf16 v[38:41], v[150:153], v[138:141], v[38:41]
	v_mfma_f32_16x16x32_bf16 v[42:45], v[154:157], v[138:141], v[42:45]
	v_mfma_f32_16x16x32_bf16 v[46:49], v[158:161], v[138:141], v[46:49]
	v_mfma_f32_16x16x32_bf16 v[50:53], v[146:149], v[142:145], v[50:53]
	v_mfma_f32_16x16x32_bf16 v[54:57], v[150:153], v[142:145], v[54:57]
	v_mfma_f32_16x16x32_bf16 v[58:61], v[154:157], v[142:145], v[58:61]
	v_mfma_f32_16x16x32_bf16 v[62:65], v[158:161], v[142:145], v[62:65]
	v_mfma_f32_16x16x32_bf16 v[2:5], v[228:231], v[212:215], v[2:5]
	v_mfma_f32_16x16x32_bf16 v[6:9], v[232:235], v[212:215], v[6:9]
	v_mfma_f32_16x16x32_bf16 v[10:13], v[236:239], v[212:215], v[10:13]
	v_mfma_f32_16x16x32_bf16 v[14:17], v[240:243], v[212:215], v[14:17]
	v_mfma_f32_16x16x32_bf16 v[18:21], v[228:231], v[216:219], v[18:21]
	v_mfma_f32_16x16x32_bf16 v[22:25], v[232:235], v[216:219], v[22:25]
	v_mfma_f32_16x16x32_bf16 v[26:29], v[236:239], v[216:219], v[26:29]
	v_mfma_f32_16x16x32_bf16 v[30:33], v[240:243], v[216:219], v[30:33]
	v_mfma_f32_16x16x32_bf16 v[34:37], v[228:231], v[220:223], v[34:37]
	v_mfma_f32_16x16x32_bf16 v[38:41], v[232:235], v[220:223], v[38:41]
	v_mfma_f32_16x16x32_bf16 v[42:45], v[236:239], v[220:223], v[42:45]
	v_mfma_f32_16x16x32_bf16 v[46:49], v[240:243], v[220:223], v[46:49]
	v_mfma_f32_16x16x32_bf16 v[50:53], v[228:231], v[224:227], v[50:53]
	v_mfma_f32_16x16x32_bf16 v[54:57], v[232:235], v[224:227], v[54:57]
	v_mfma_f32_16x16x32_bf16 v[58:61], v[236:239], v[224:227], v[58:61]
	v_mfma_f32_16x16x32_bf16 v[62:65], v[240:243], v[224:227], v[62:65]
	s_waitcnt vmcnt(6)
	s_barrier
	v_add_u32_e32 v204, 0x18000, v200
	v_add_u32_e32 v205, 0x18000, v202
	ds_read_b128 v[130:133], v204 offset:0
	ds_read_b128 v[134:137], v204 offset:2048
	ds_read_b128 v[138:141], v204 offset:4096
	ds_read_b128 v[142:145], v204 offset:6144
	ds_read_b128 v[146:149], v205 offset:0
	ds_read_b128 v[150:153], v205 offset:2048
	ds_read_b128 v[154:157], v205 offset:4096
	ds_read_b128 v[158:161], v205 offset:6144
	v_add_u32_e32 v204, 0x18000, v201
	v_add_u32_e32 v205, 0x18000, v203
	ds_read_b128 v[212:215], v204 offset:0
	ds_read_b128 v[216:219], v204 offset:2048
	ds_read_b128 v[220:223], v204 offset:4096
	ds_read_b128 v[224:227], v204 offset:6144
	ds_read_b128 v[228:231], v205 offset:0
	ds_read_b128 v[232:235], v205 offset:2048
	ds_read_b128 v[236:239], v205 offset:4096
	ds_read_b128 v[240:243], v205 offset:6144
	s_waitcnt lgkmcnt(0)
	s_barrier
	v_mfma_f32_16x16x32_bf16 v[2:5], v[146:149], v[130:133], v[2:5]
	v_mfma_f32_16x16x32_bf16 v[6:9], v[150:153], v[130:133], v[6:9]
	v_mfma_f32_16x16x32_bf16 v[10:13], v[154:157], v[130:133], v[10:13]
	v_mfma_f32_16x16x32_bf16 v[14:17], v[158:161], v[130:133], v[14:17]
	v_mfma_f32_16x16x32_bf16 v[18:21], v[146:149], v[134:137], v[18:21]
	v_mfma_f32_16x16x32_bf16 v[22:25], v[150:153], v[134:137], v[22:25]
	v_mfma_f32_16x16x32_bf16 v[26:29], v[154:157], v[134:137], v[26:29]
	v_mfma_f32_16x16x32_bf16 v[30:33], v[158:161], v[134:137], v[30:33]
	v_mfma_f32_16x16x32_bf16 v[34:37], v[146:149], v[138:141], v[34:37]
	v_mfma_f32_16x16x32_bf16 v[38:41], v[150:153], v[138:141], v[38:41]
	v_mfma_f32_16x16x32_bf16 v[42:45], v[154:157], v[138:141], v[42:45]
	v_mfma_f32_16x16x32_bf16 v[46:49], v[158:161], v[138:141], v[46:49]
	v_mfma_f32_16x16x32_bf16 v[50:53], v[146:149], v[142:145], v[50:53]
	v_mfma_f32_16x16x32_bf16 v[54:57], v[150:153], v[142:145], v[54:57]
	v_mfma_f32_16x16x32_bf16 v[58:61], v[154:157], v[142:145], v[58:61]
	v_mfma_f32_16x16x32_bf16 v[62:65], v[158:161], v[142:145], v[62:65]
	v_mfma_f32_16x16x32_bf16 v[2:5], v[228:231], v[212:215], v[2:5]
	v_mfma_f32_16x16x32_bf16 v[6:9], v[232:235], v[212:215], v[6:9]
	v_mfma_f32_16x16x32_bf16 v[10:13], v[236:239], v[212:215], v[10:13]
	v_mfma_f32_16x16x32_bf16 v[14:17], v[240:243], v[212:215], v[14:17]
	v_mfma_f32_16x16x32_bf16 v[18:21], v[228:231], v[216:219], v[18:21]
	v_mfma_f32_16x16x32_bf16 v[22:25], v[232:235], v[216:219], v[22:25]
	v_mfma_f32_16x16x32_bf16 v[26:29], v[236:239], v[216:219], v[26:29]
	v_mfma_f32_16x16x32_bf16 v[30:33], v[240:243], v[216:219], v[30:33]
	v_mfma_f32_16x16x32_bf16 v[34:37], v[228:231], v[220:223], v[34:37]
	v_mfma_f32_16x16x32_bf16 v[38:41], v[232:235], v[220:223], v[38:41]
	v_mfma_f32_16x16x32_bf16 v[42:45], v[236:239], v[220:223], v[42:45]
	v_mfma_f32_16x16x32_bf16 v[46:49], v[240:243], v[220:223], v[46:49]
	v_mfma_f32_16x16x32_bf16 v[50:53], v[228:231], v[224:227], v[50:53]
	v_mfma_f32_16x16x32_bf16 v[54:57], v[232:235], v[224:227], v[54:57]
	v_mfma_f32_16x16x32_bf16 v[58:61], v[236:239], v[224:227], v[58:61]
	v_mfma_f32_16x16x32_bf16 v[62:65], v[240:243], v[224:227], v[62:65]
	s_waitcnt vmcnt(0)
	s_barrier
	v_add_u32_e32 v204, 0x0, v200
	v_add_u32_e32 v205, 0x0, v202
	ds_read_b128 v[130:133], v204 offset:0
	ds_read_b128 v[134:137], v204 offset:2048
	ds_read_b128 v[138:141], v204 offset:4096
	ds_read_b128 v[142:145], v204 offset:6144
	ds_read_b128 v[146:149], v205 offset:0
	ds_read_b128 v[150:153], v205 offset:2048
	ds_read_b128 v[154:157], v205 offset:4096
	ds_read_b128 v[158:161], v205 offset:6144
	v_add_u32_e32 v204, 0x0, v201
	v_add_u32_e32 v205, 0x0, v203
	ds_read_b128 v[212:215], v204 offset:0
	ds_read_b128 v[216:219], v204 offset:2048
	ds_read_b128 v[220:223], v204 offset:4096
	ds_read_b128 v[224:227], v204 offset:6144
	ds_read_b128 v[228:231], v205 offset:0
	ds_read_b128 v[232:235], v205 offset:2048
	ds_read_b128 v[236:239], v205 offset:4096
	ds_read_b128 v[240:243], v205 offset:6144
	s_waitcnt lgkmcnt(0)
	s_barrier
	v_mfma_f32_16x16x32_bf16 v[2:5], v[146:149], v[130:133], v[2:5]
	v_mfma_f32_16x16x32_bf16 v[6:9], v[150:153], v[130:133], v[6:9]
	v_mfma_f32_16x16x32_bf16 v[10:13], v[154:157], v[130:133], v[10:13]
	v_mfma_f32_16x16x32_bf16 v[14:17], v[158:161], v[130:133], v[14:17]
	v_mfma_f32_16x16x32_bf16 v[18:21], v[146:149], v[134:137], v[18:21]
	v_mfma_f32_16x16x32_bf16 v[22:25], v[150:153], v[134:137], v[22:25]
	v_mfma_f32_16x16x32_bf16 v[26:29], v[154:157], v[134:137], v[26:29]
	v_mfma_f32_16x16x32_bf16 v[30:33], v[158:161], v[134:137], v[30:33]
	v_mfma_f32_16x16x32_bf16 v[34:37], v[146:149], v[138:141], v[34:37]
	v_mfma_f32_16x16x32_bf16 v[38:41], v[150:153], v[138:141], v[38:41]
	v_mfma_f32_16x16x32_bf16 v[42:45], v[154:157], v[138:141], v[42:45]
	v_mfma_f32_16x16x32_bf16 v[46:49], v[158:161], v[138:141], v[46:49]
	v_mfma_f32_16x16x32_bf16 v[50:53], v[146:149], v[142:145], v[50:53]
	v_mfma_f32_16x16x32_bf16 v[54:57], v[150:153], v[142:145], v[54:57]
	v_mfma_f32_16x16x32_bf16 v[58:61], v[154:157], v[142:145], v[58:61]
	v_mfma_f32_16x16x32_bf16 v[62:65], v[158:161], v[142:145], v[62:65]
	v_mfma_f32_16x16x32_bf16 v[2:5], v[228:231], v[212:215], v[2:5]
	v_mfma_f32_16x16x32_bf16 v[6:9], v[232:235], v[212:215], v[6:9]
	v_mfma_f32_16x16x32_bf16 v[10:13], v[236:239], v[212:215], v[10:13]
	v_mfma_f32_16x16x32_bf16 v[14:17], v[240:243], v[212:215], v[14:17]
	v_mfma_f32_16x16x32_bf16 v[18:21], v[228:231], v[216:219], v[18:21]
	v_mfma_f32_16x16x32_bf16 v[22:25], v[232:235], v[216:219], v[22:25]
	v_mfma_f32_16x16x32_bf16 v[26:29], v[236:239], v[216:219], v[26:29]
	v_mfma_f32_16x16x32_bf16 v[30:33], v[240:243], v[216:219], v[30:33]
	v_mfma_f32_16x16x32_bf16 v[34:37], v[228:231], v[220:223], v[34:37]
	v_mfma_f32_16x16x32_bf16 v[38:41], v[232:235], v[220:223], v[38:41]
	v_mfma_f32_16x16x32_bf16 v[42:45], v[236:239], v[220:223], v[42:45]
	v_mfma_f32_16x16x32_bf16 v[46:49], v[240:243], v[220:223], v[46:49]
	v_mfma_f32_16x16x32_bf16 v[50:53], v[228:231], v[224:227], v[50:53]
	v_mfma_f32_16x16x32_bf16 v[54:57], v[232:235], v[224:227], v[54:57]
	v_mfma_f32_16x16x32_bf16 v[58:61], v[236:239], v[224:227], v[58:61]
	v_mfma_f32_16x16x32_bf16 v[62:65], v[240:243], v[224:227], v[62:65]
	s_barrier
	s_branch .Lop_join

.LBB0_727:
	s_mov_b64 s[2:3], s[46:47]
	s_add_i32 s18, s2, 1
	s_cmp_ge_i32 s18, s3
	v_readlane_b32 s30, v254, 6
	v_readlane_b32 s38, v254, 8
	v_readlane_b32 s56, v254, 22
	v_readlane_b32 s31, v254, 7
	v_readlane_b32 s39, v254, 9
	v_readlane_b32 s57, v254, 23
	s_cbranch_scc1 .LBB0_781
	s_cmp_eq_u32 s2, 5
	s_cbranch_scc1 .LBB0_781
	s_cmp_eq_u32 s2, 14
	s_cbranch_scc1 .LBB0_781
	s_cmp_eq_u32 s2, 9
	s_cbranch_scc1 .LBB0_781
	s_cmp_eq_u32 s2, 18
	s_cbranch_scc1 .LBB0_781
	s_cmp_eq_u32 s2, 4
	s_cbranch_scc1 .LBB0_781
	s_cmp_eq_u32 s2, 13
	s_cbranch_scc1 .LBB0_781
	s_cmp_eq_u32 s2, 0
	s_cbranch_scc1 .LBB0_781
	s_waitcnt vmcnt(0)
	s_waitcnt lgkmcnt(0)
	s_barrier
	s_mov_b64 s[2:3], exec
	v_readlane_b32 s4, v253, 7
	v_readlane_b32 s5, v253, 8
	s_and_b64 s[4:5], s[2:3], s[4:5]
	s_mov_b64 exec, s[4:5]
	s_cbranch_execz .LBB0_780
	buffer_inv sc1
	s_add_i32 s13, 0, 0x24000
	s_mov_b64 s[4:5], src_shared_base
	s_cmp_lg_u32 s13, -1
	s_cselect_b32 s4, s13, 0
	s_cselect_b32 s6, s5, 0
	s_add_i32 s12, 0, 0x24004
	s_cmp_lg_u32 s12, -1
	v_mov_b32_e32 v2, s4
	v_mov_b32_e32 v3, s6
	s_cselect_b32 s4, s12, 0
	s_cselect_b32 s5, s5, 0
	s_waitcnt vmcnt(0) expcnt(0) lgkmcnt(0)
	s_and_b32 s4, s101, 0xffff
	v_mov_b32_e32 v4, s4
	v_mov_b32_e32 v2, s4
	v_mov_b32_e32 v3, s5
	s_lshr_b32 s4, s101, 16
	v_mov_b32_e32 v2, s4
	s_waitcnt vmcnt(0) lgkmcnt(0)
	v_cmp_eq_u32_e32 vcc, 0, v4
	s_and_saveexec_b64 s[4:5], vcc
	s_cbranch_execz .LBB0_744
	s_mov_b32 s14, 1
	s_branch .LBB0_732

.LBB0_759:
	s_or_b64 exec, exec, s[6:7]
	s_waitcnt vmcnt(0) lgkmcnt(0)
	s_waitcnt vmcnt(0)

.LBB0_777:
	s_or_b64 exec, exec, s[4:5]
	s_mov_b64 s[4:5], exec
	v_mbcnt_lo_u32_b32 v2, s4, 0
	v_mbcnt_hi_u32_b32 v2, s5, v2
	v_cmp_eq_u32_e32 vcc, 0, v2
	s_waitcnt vmcnt(0)
	s_and_saveexec_b64 s[6:7], vcc
	s_cbranch_execz .LBB0_779
	s_bcnt1_i32_b64 s4, s[4:5]
	v_mov_b32_e32 v2, s4
	v_readlane_b32 s4, v253, 44
	v_readlane_b32 s5, v253, 45
	s_nop 4
